# v072 + RG-LRU gate epilogue: log2e scalings folded into per-block pre-scaled bias/sp constants (fma+min instead of add+min+mul; r*sp' instead of r*sp*log2e): 3 fewer f32 VALU per element, same math
# speedup vs baseline: 1.0047x; 1.0047x over previous
; #define LAS __attribute__((address_space(3)))
; DI u32x4 pack8f(const float (&f)[8]) { u32x4 r; r[0] = pk2(f[0], f[1]); r[1] = pk2(f[2], f[3]); r[2] = pk2(f[4], f[5]); r[3] = pk2(f[6], f[7]); return r; }
; DI void phase_rglru(const Params& p, unsigned char* shm) {
;     ...
; #pragma unroll
;             for (int j = 0; j < 3; ++j) {
;                 const int q = tid + 512 * j, cc = q % 24;
;                 float a8[8];
;                 { const f32x4 b0 = *(const LAS f32x4*)(cw + 768 + 8 * cc), b1 = *(const LAS f32x4*)(cw + 768 + 8 * cc + 4);
; #pragma unroll
;                   for (int e = 0; e < 4; ++e) { a8[e] = b0[e]; a8[4 + e] = b1[e]; } }
; #pragma unroll
;                 for (int jj = 0; jj < 4; ++jj) {
;                     float xin[8]; { const u32x4 xraw = *(const LAS u32x4*)(lds + XR + jj * TR + loff[j]); unpack8(xraw, xin); }
;                     const f32x4 w0 = *(const LAS f32x4*)(cw + jj * 192 + 8 * cc), w1 = *(const LAS f32x4*)(cw + jj * 192 + 8 * cc + 4);
; #pragma unroll
;                     for (int e = 0; e < 4; ++e) { a8[e] += w0[e] * xin[e]; a8[4 + e] += w1[e] * xin[4 + e]; }
;                 }
;                 *(LAS u32x4*)(lds + XC + loff[j]) = pack8f(a8);
;             }
.LBB0_845:
	s_waitcnt lgkmcnt(0)
	s_barrier
	ds_read_b128 v[120:123], v178
	ds_read_b128 v[124:127], v178 offset:16
	ds_read_b128 v[128:131], v201
	ds_read_b128 v[132:135], v179
	ds_read_b128 v[136:139], v179 offset:16
	ds_read_b128 v[140:143], v201 offset:400
	ds_read_b128 v[144:147], v179 offset:768
	ds_read_b128 v[148:151], v179 offset:784
	ds_read_b128 v[210:213], v201 offset:800
	ds_read_b128 v[214:217], v179 offset:1536
	ds_read_b128 v[218:221], v179 offset:1552
	ds_read_b128 v[222:225], v201 offset:1200
	ds_read_b128 v[226:229], v179 offset:2304
	ds_read_b128 v[230:233], v179 offset:2320
	s_waitcnt lgkmcnt(11)
	v_lshlrev_b32_e32 v170, 16, v128
	v_and_b32_e32 v171, 0xffff0000, v128
	v_lshlrev_b32_e32 v128, 16, v129
	v_and_b32_e32 v129, 0xffff0000, v129
	s_waitcnt lgkmcnt(10)
	v_pk_fma_f32 v[120:121], v[132:133], v[170:171], v[120:121]
	s_waitcnt lgkmcnt(8)
	v_lshlrev_b32_e32 v132, 16, v140
	v_and_b32_e32 v133, 0xffff0000, v140
	v_pk_fma_f32 v[122:123], v[134:135], v[128:129], v[122:123]
	v_lshlrev_b32_e32 v128, 16, v141
	v_and_b32_e32 v129, 0xffff0000, v141
	s_waitcnt lgkmcnt(7)
	v_pk_fma_f32 v[120:121], v[144:145], v[132:133], v[120:121]
	s_waitcnt lgkmcnt(5)
	v_lshlrev_b32_e32 v132, 16, v210
	v_and_b32_e32 v133, 0xffff0000, v210
	v_pk_fma_f32 v[122:123], v[146:147], v[128:129], v[122:123]
	v_lshlrev_b32_e32 v128, 16, v211
	v_and_b32_e32 v129, 0xffff0000, v211
	s_waitcnt lgkmcnt(4)
	v_pk_fma_f32 v[120:121], v[214:215], v[132:133], v[120:121]
	s_waitcnt lgkmcnt(2)
	v_lshlrev_b32_e32 v132, 16, v222
	v_and_b32_e32 v133, 0xffff0000, v222
	v_pk_fma_f32 v[122:123], v[216:217], v[128:129], v[122:123]
	v_lshlrev_b32_e32 v128, 16, v223
	v_and_b32_e32 v129, 0xffff0000, v223
	s_waitcnt lgkmcnt(1)
	v_pk_fma_f32 v[120:121], v[226:227], v[132:133], v[120:121]
	v_lshlrev_b32_e32 v132, 16, v130
	v_and_b32_e32 v133, 0xffff0000, v130
	v_pk_fma_f32 v[122:123], v[228:229], v[128:129], v[122:123]
	v_lshlrev_b32_e32 v128, 16, v131
	v_and_b32_e32 v129, 0xffff0000, v131
	v_pk_fma_f32 v[124:125], v[136:137], v[132:133], v[124:125]
	v_lshlrev_b32_e32 v132, 16, v142
	v_and_b32_e32 v133, 0xffff0000, v142
	v_pk_fma_f32 v[126:127], v[138:139], v[128:129], v[126:127]
	v_lshlrev_b32_e32 v128, 16, v143
	v_and_b32_e32 v129, 0xffff0000, v143
	v_pk_fma_f32 v[124:125], v[148:149], v[132:133], v[124:125]
	v_lshlrev_b32_e32 v132, 16, v212
	v_and_b32_e32 v133, 0xffff0000, v212
	v_pk_fma_f32 v[126:127], v[150:151], v[128:129], v[126:127]
	v_lshlrev_b32_e32 v128, 16, v213
	v_and_b32_e32 v129, 0xffff0000, v213
	v_pk_fma_f32 v[124:125], v[218:219], v[132:133], v[124:125]
	v_lshlrev_b32_e32 v132, 16, v224
	v_and_b32_e32 v133, 0xffff0000, v224
	v_pk_fma_f32 v[126:127], v[220:221], v[128:129], v[126:127]
	v_lshlrev_b32_e32 v128, 16, v225
	v_and_b32_e32 v129, 0xffff0000, v225
	s_waitcnt lgkmcnt(0)
	v_pk_fma_f32 v[124:125], v[230:231], v[132:133], v[124:125]
	v_pk_fma_f32 v[126:127], v[232:233], v[128:129], v[126:127]
	v_cvt_pk_bf16_f32 v120, v120, v121
	v_cvt_pk_bf16_f32 v121, v122, v123
	v_cvt_pk_bf16_f32 v122, v124, v125
	v_cvt_pk_bf16_f32 v123, v126, v127
	ds_write_b128 v201, v[120:123] offset:26880
	ds_read_b128 v[120:123], v180
	ds_read_b128 v[124:127], v180 offset:16
	ds_read_b128 v[128:131], v202
	ds_read_b128 v[132:135], v181
	ds_read_b128 v[136:139], v181 offset:16
	ds_read_b128 v[140:143], v202 offset:400
	ds_read_b128 v[144:147], v181 offset:768
	ds_read_b128 v[148:151], v181 offset:784
	ds_read_b128 v[210:213], v202 offset:800
	ds_read_b128 v[214:217], v181 offset:1536
	ds_read_b128 v[218:221], v181 offset:1552
	ds_read_b128 v[222:225], v202 offset:1200
	ds_read_b128 v[226:229], v181 offset:2304
	ds_read_b128 v[230:233], v181 offset:2320
	s_waitcnt lgkmcnt(11)
	v_lshlrev_b32_e32 v170, 16, v128
	v_and_b32_e32 v171, 0xffff0000, v128
	v_lshlrev_b32_e32 v128, 16, v129
	v_and_b32_e32 v129, 0xffff0000, v129
	s_waitcnt lgkmcnt(10)
	v_pk_fma_f32 v[120:121], v[132:133], v[170:171], v[120:121]
	s_waitcnt lgkmcnt(8)
	v_lshlrev_b32_e32 v132, 16, v140
	v_and_b32_e32 v133, 0xffff0000, v140
	v_pk_fma_f32 v[122:123], v[134:135], v[128:129], v[122:123]
	v_lshlrev_b32_e32 v128, 16, v141
	v_and_b32_e32 v129, 0xffff0000, v141
	s_waitcnt lgkmcnt(7)
	v_pk_fma_f32 v[120:121], v[144:145], v[132:133], v[120:121]
	s_waitcnt lgkmcnt(5)
	v_lshlrev_b32_e32 v132, 16, v210
	v_and_b32_e32 v133, 0xffff0000, v210
	v_pk_fma_f32 v[122:123], v[146:147], v[128:129], v[122:123]
	v_lshlrev_b32_e32 v128, 16, v211
	v_and_b32_e32 v129, 0xffff0000, v211
	s_waitcnt lgkmcnt(4)
	v_pk_fma_f32 v[120:121], v[214:215], v[132:133], v[120:121]
	s_waitcnt lgkmcnt(2)
	v_lshlrev_b32_e32 v132, 16, v222
	v_and_b32_e32 v133, 0xffff0000, v222
	v_pk_fma_f32 v[122:123], v[216:217], v[128:129], v[122:123]
	v_lshlrev_b32_e32 v128, 16, v223
	v_and_b32_e32 v129, 0xffff0000, v223
	s_waitcnt lgkmcnt(1)
	v_pk_fma_f32 v[120:121], v[226:227], v[132:133], v[120:121]
	v_lshlrev_b32_e32 v132, 16, v130
	v_and_b32_e32 v133, 0xffff0000, v130
	v_pk_fma_f32 v[122:123], v[228:229], v[128:129], v[122:123]
	v_lshlrev_b32_e32 v128, 16, v131
	v_and_b32_e32 v129, 0xffff0000, v131
	v_pk_fma_f32 v[124:125], v[136:137], v[132:133], v[124:125]
	v_lshlrev_b32_e32 v132, 16, v142
	v_and_b32_e32 v133, 0xffff0000, v142
	v_pk_fma_f32 v[126:127], v[138:139], v[128:129], v[126:127]
	v_lshlrev_b32_e32 v128, 16, v143
	v_and_b32_e32 v129, 0xffff0000, v143
	v_pk_fma_f32 v[124:125], v[148:149], v[132:133], v[124:125]
	v_lshlrev_b32_e32 v132, 16, v212
	v_and_b32_e32 v133, 0xffff0000, v212
	v_pk_fma_f32 v[126:127], v[150:151], v[128:129], v[126:127]
	v_lshlrev_b32_e32 v128, 16, v213
	v_and_b32_e32 v129, 0xffff0000, v213
	v_pk_fma_f32 v[124:125], v[218:219], v[132:133], v[124:125]
	v_lshlrev_b32_e32 v132, 16, v224
	v_and_b32_e32 v133, 0xffff0000, v224
	v_pk_fma_f32 v[126:127], v[220:221], v[128:129], v[126:127]
	v_lshlrev_b32_e32 v128, 16, v225
	v_and_b32_e32 v129, 0xffff0000, v225
	s_waitcnt lgkmcnt(0)
; #define LAS __attribute__((address_space(3)))
; DI u32x4 pack8f(const float (&f)[8]) { u32x4 r; r[0] = pk2(f[0], f[1]); r[1] = pk2(f[2], f[3]); r[2] = pk2(f[4], f[5]); r[3] = pk2(f[6], f[7]); return r; }
; DI void phase_rglru(const Params& p, unsigned char* shm) {
;     ...
;                 *(LAS u32x4*)(lds + XC + loff[j]) = pack8f(a8);
;             }
;             __syncthreads();
;             {
; #pragma unroll
;                 for (int u = 0; u < 2; ++u) {
;                     if (u == 1 && w >= 4) break;
;                     f32x4 acc[4][2];
; #pragma unroll
;                     for (int mt = 0; mt < 4; ++mt) { acc[mt][0] = (f32x4){0.f, 0.f, 0.f, 0.f}; acc[mt][1] = (f32x4){0.f, 0.f, 0.f, 0.f}; }
; #pragma unroll
;                     for (int kk = 0; kk < 6; ++kk)
; #pragma unroll
;                         for (int mt = 0; mt < 4; ++mt) {
;                             const bf16x8 af = *(const LAS bf16x8*)(lds + XC + (16 * mt + fr) * TR + (32 * kk + 8 * fq) * 2);
;                             acc[mt][0] = __builtin_amdgcn_mfma_f32_16x16x32_bf16(af, Bf[u][kk], acc[mt][0], 0, 0, 0);
;                             acc[mt][1] = __builtin_amdgcn_mfma_f32_16x16x32_bf16(af, Bf[2 + u][kk], acc[mt][1], 0, 0, 0);
;                         }
	v_pk_fma_f32 v[124:125], v[230:231], v[132:133], v[124:125]
	v_pk_fma_f32 v[126:127], v[232:233], v[128:129], v[126:127]
	v_cvt_pk_bf16_f32 v120, v120, v121
	v_cvt_pk_bf16_f32 v121, v122, v123
	v_cvt_pk_bf16_f32 v122, v124, v125
	v_cvt_pk_bf16_f32 v123, v126, v127
	ds_write_b128 v202, v[120:123] offset:26880
	ds_read_b128 v[120:123], v182
	ds_read_b128 v[124:127], v182 offset:16
	ds_read_b128 v[128:131], v203
	ds_read_b128 v[132:135], v183
	ds_read_b128 v[136:139], v183 offset:16
	ds_read_b128 v[140:143], v203 offset:400
	ds_read_b128 v[144:147], v183 offset:768
	ds_read_b128 v[148:151], v183 offset:784
	ds_read_b128 v[210:213], v203 offset:800
	ds_read_b128 v[214:217], v183 offset:1536
	ds_read_b128 v[218:221], v183 offset:1552
	ds_read_b128 v[222:225], v203 offset:1200
	ds_read_b128 v[226:229], v183 offset:2304
	ds_read_b128 v[230:233], v183 offset:2320
	s_waitcnt lgkmcnt(11)
	v_lshlrev_b32_e32 v170, 16, v128
	v_and_b32_e32 v171, 0xffff0000, v128
	v_lshlrev_b32_e32 v128, 16, v129
	v_and_b32_e32 v129, 0xffff0000, v129
	s_waitcnt lgkmcnt(10)
	v_pk_fma_f32 v[120:121], v[132:133], v[170:171], v[120:121]
	s_waitcnt lgkmcnt(8)
	v_lshlrev_b32_e32 v132, 16, v140
	v_and_b32_e32 v133, 0xffff0000, v140
	v_pk_fma_f32 v[122:123], v[134:135], v[128:129], v[122:123]
	v_lshlrev_b32_e32 v128, 16, v141
	v_and_b32_e32 v129, 0xffff0000, v141
	s_waitcnt lgkmcnt(7)
	v_pk_fma_f32 v[120:121], v[144:145], v[132:133], v[120:121]
	s_waitcnt lgkmcnt(5)
	v_lshlrev_b32_e32 v132, 16, v210
	v_and_b32_e32 v133, 0xffff0000, v210
	v_pk_fma_f32 v[122:123], v[146:147], v[128:129], v[122:123]
	v_lshlrev_b32_e32 v128, 16, v211
	v_and_b32_e32 v129, 0xffff0000, v211
	s_waitcnt lgkmcnt(4)
	v_pk_fma_f32 v[120:121], v[214:215], v[132:133], v[120:121]
	s_waitcnt lgkmcnt(2)
	v_lshlrev_b32_e32 v132, 16, v222
	v_and_b32_e32 v133, 0xffff0000, v222
	v_pk_fma_f32 v[122:123], v[216:217], v[128:129], v[122:123]
	v_lshlrev_b32_e32 v128, 16, v223
	v_and_b32_e32 v129, 0xffff0000, v223
	s_waitcnt lgkmcnt(1)
	v_pk_fma_f32 v[120:121], v[226:227], v[132:133], v[120:121]
	v_lshlrev_b32_e32 v132, 16, v130
	v_and_b32_e32 v133, 0xffff0000, v130
	v_pk_fma_f32 v[122:123], v[228:229], v[128:129], v[122:123]
	v_lshlrev_b32_e32 v128, 16, v131
	v_and_b32_e32 v129, 0xffff0000, v131
	v_pk_fma_f32 v[124:125], v[136:137], v[132:133], v[124:125]
	v_lshlrev_b32_e32 v132, 16, v142
	v_and_b32_e32 v133, 0xffff0000, v142
	v_pk_fma_f32 v[126:127], v[138:139], v[128:129], v[126:127]
	v_lshlrev_b32_e32 v128, 16, v143
	v_and_b32_e32 v129, 0xffff0000, v143
	v_pk_fma_f32 v[124:125], v[148:149], v[132:133], v[124:125]
	v_lshlrev_b32_e32 v132, 16, v212
	v_and_b32_e32 v133, 0xffff0000, v212
	v_pk_fma_f32 v[126:127], v[150:151], v[128:129], v[126:127]
	v_lshlrev_b32_e32 v128, 16, v213
	v_and_b32_e32 v129, 0xffff0000, v213
	v_pk_fma_f32 v[124:125], v[218:219], v[132:133], v[124:125]
	v_lshlrev_b32_e32 v132, 16, v224
	v_and_b32_e32 v133, 0xffff0000, v224
	v_pk_fma_f32 v[126:127], v[220:221], v[128:129], v[126:127]
	v_lshlrev_b32_e32 v128, 16, v225
	v_and_b32_e32 v129, 0xffff0000, v225
	s_waitcnt lgkmcnt(0)
	v_pk_fma_f32 v[124:125], v[230:231], v[132:133], v[124:125]
	v_pk_fma_f32 v[126:127], v[232:233], v[128:129], v[126:127]
	v_cvt_pk_bf16_f32 v120, v120, v121
	v_cvt_pk_bf16_f32 v121, v122, v123
	v_cvt_pk_bf16_f32 v122, v124, v125
	v_cvt_pk_bf16_f32 v123, v126, v127
	ds_write_b128 v203, v[120:123] offset:26880
	s_waitcnt lgkmcnt(0)
	s_barrier
	ds_read_b128 v[120:123], v204 offset:26880
	ds_read_b128 v[124:127], v204 offset:33280
	ds_read_b128 v[128:131], v204 offset:39680
	ds_read_b128 v[132:135], v204 offset:46080
	ds_read_b128 v[226:229], v204 offset:26944
	s_waitcnt lgkmcnt(4)
	v_mfma_f32_16x16x32_bf16 v[148:151], v[120:123], v[0:3], 0
	v_mfma_f32_16x16x32_bf16 v[144:147], v[120:123], v[48:51], 0
	ds_read_b128 v[230:233], v204 offset:33344
	s_waitcnt lgkmcnt(4)
	v_mfma_f32_16x16x32_bf16 v[140:143], v[124:127], v[0:3], 0
	v_mfma_f32_16x16x32_bf16 v[136:139], v[124:127], v[48:51], 0
	ds_read_b128 v[120:123], v204 offset:39744
	s_waitcnt lgkmcnt(4)
	v_mfma_f32_16x16x32_bf16 v[214:217], v[128:131], v[0:3], 0
	v_mfma_f32_16x16x32_bf16 v[210:213], v[128:131], v[48:51], 0
	ds_read_b128 v[124:127], v204 offset:46144
	s_waitcnt lgkmcnt(4)
	v_mfma_f32_16x16x32_bf16 v[218:221], v[132:135], v[0:3], 0
	v_mfma_f32_16x16x32_bf16 v[222:225], v[132:135], v[48:51], 0
	ds_read_b128 v[128:131], v204 offset:27008
	s_waitcnt lgkmcnt(4)
	v_mfma_f32_16x16x32_bf16 v[148:151], v[226:229], v[4:7], v[148:151]
	v_mfma_f32_16x16x32_bf16 v[144:147], v[226:229], v[52:55], v[144:147]
	ds_read_b128 v[132:135], v204 offset:33408
	s_waitcnt lgkmcnt(4)
	v_mfma_f32_16x16x32_bf16 v[140:143], v[230:233], v[4:7], v[140:143]
	v_mfma_f32_16x16x32_bf16 v[136:139], v[230:233], v[52:55], v[136:139]
	ds_read_b128 v[226:229], v204 offset:39808
	s_waitcnt lgkmcnt(4)
	v_mfma_f32_16x16x32_bf16 v[214:217], v[120:123], v[4:7], v[214:217]
	v_mfma_f32_16x16x32_bf16 v[210:213], v[120:123], v[52:55], v[210:213]
	ds_read_b128 v[230:233], v204 offset:46208
	s_waitcnt lgkmcnt(4)
	v_mfma_f32_16x16x32_bf16 v[218:221], v[124:127], v[4:7], v[218:221]
	v_mfma_f32_16x16x32_bf16 v[222:225], v[124:127], v[52:55], v[222:225]
	ds_read_b128 v[120:123], v204 offset:27072
	s_waitcnt lgkmcnt(4)
	v_mfma_f32_16x16x32_bf16 v[148:151], v[128:131], v[8:11], v[148:151]
	v_mfma_f32_16x16x32_bf16 v[144:147], v[128:131], v[56:59], v[144:147]
	ds_read_b128 v[124:127], v204 offset:33472
	s_waitcnt lgkmcnt(4)
	v_mfma_f32_16x16x32_bf16 v[140:143], v[132:135], v[8:11], v[140:143]
	v_mfma_f32_16x16x32_bf16 v[136:139], v[132:135], v[56:59], v[136:139]
	ds_read_b128 v[128:131], v204 offset:39872
	s_waitcnt lgkmcnt(4)
; #define LAS __attribute__((address_space(3)))
; DI unsigned pk2(float a, float b) { f32x2 v = {a, b}; bf2_t r = __builtin_convertvector(v, bf2_t); return __builtin_bit_cast(unsigned, r); }
; DI void phase_rglru(const Params& p, unsigned char* shm) {
;     ...
;                     for (int kk = 0; kk < 6; ++kk)
; #pragma unroll
;                         for (int mt = 0; mt < 4; ++mt) {
;                             const bf16x8 af = *(const LAS bf16x8*)(lds + XC + (16 * mt + fr) * TR + (32 * kk + 8 * fq) * 2);
;                             acc[mt][0] = __builtin_amdgcn_mfma_f32_16x16x32_bf16(af, Bf[u][kk], acc[mt][0], 0, 0, 0);
;                             acc[mt][1] = __builtin_amdgcn_mfma_f32_16x16x32_bf16(af, Bf[2 + u][kk], acc[mt][1], 0, 0, 0);
;                         }
;                     const int ch = chb + 16 * u + fr;
;                     const float ba = gb[ch], bx = gb[192 + ch], sp = gb[384 + ch];
; #pragma unroll
;                     for (int mt = 0; mt < 4; ++mt)
; #pragma unroll
;                         for (int j = 0; j < 4; ++j) {
;                             const int t = 16 * mt + 4 * fq + j;
;                             const float ea = 1.f + __expf(fminf(-(acc[mt][0][j] + ba), 40.f)), ex = 1.f + __expf(fminf(-(acc[mt][1][j] + bx), 40.f));
;                             const float inv = __builtin_amdgcn_rcpf(ea * ex);
;                             const float r = inv * ex, ig = inv * ea;
;                             const float av = __expf(r * sp), om = 1.f - av;
;                             const float xcv = __uint_as_float((unsigned)*(const LAS bf16_t*)(lds + XC + t * TR + ch * 2) << 16);
;                             const float bt = __builtin_amdgcn_sqrtf(fmaxf(om * (1.f + av), 0.f)) * (ig * xcv);
;                             *(LAS bf16_t*)(lds + LAo + t * TR + ch * 2) = (bf16_t)(pk2(om, 0.f) & 0xffffu);
;                             *(LAS bf16_t*)(lds + BTo + t * TR + ch * 2) = (bf16_t)(pk2(bt, 0.f) & 0xffffu);
;                         }
	v_mfma_f32_16x16x32_bf16 v[214:217], v[226:229], v[8:11], v[214:217]
	v_mfma_f32_16x16x32_bf16 v[210:213], v[226:229], v[56:59], v[210:213]
	ds_read_b128 v[132:135], v204 offset:46272
	s_waitcnt lgkmcnt(4)
	v_mfma_f32_16x16x32_bf16 v[218:221], v[230:233], v[8:11], v[218:221]
	v_mfma_f32_16x16x32_bf16 v[222:225], v[230:233], v[56:59], v[222:225]
	ds_read_b128 v[226:229], v204 offset:27136
	s_waitcnt lgkmcnt(4)
	v_mfma_f32_16x16x32_bf16 v[148:151], v[120:123], v[12:15], v[148:151]
	v_mfma_f32_16x16x32_bf16 v[144:147], v[120:123], v[60:63], v[144:147]
	ds_read_b128 v[230:233], v204 offset:33536
	s_waitcnt lgkmcnt(4)
	v_mfma_f32_16x16x32_bf16 v[140:143], v[124:127], v[12:15], v[140:143]
	v_mfma_f32_16x16x32_bf16 v[136:139], v[124:127], v[60:63], v[136:139]
	ds_read_b128 v[120:123], v204 offset:39936
	s_waitcnt lgkmcnt(4)
	v_mfma_f32_16x16x32_bf16 v[214:217], v[128:131], v[12:15], v[214:217]
	v_mfma_f32_16x16x32_bf16 v[210:213], v[128:131], v[60:63], v[210:213]
	ds_read_b128 v[124:127], v204 offset:46336
	s_waitcnt lgkmcnt(4)
	v_mfma_f32_16x16x32_bf16 v[218:221], v[132:135], v[12:15], v[218:221]
	v_mfma_f32_16x16x32_bf16 v[222:225], v[132:135], v[60:63], v[222:225]
	ds_read_b128 v[128:131], v204 offset:27200
	s_waitcnt lgkmcnt(4)
	v_mfma_f32_16x16x32_bf16 v[148:151], v[226:229], v[16:19], v[148:151]
	v_mfma_f32_16x16x32_bf16 v[144:147], v[226:229], v[64:67], v[144:147]
	ds_read_b128 v[132:135], v204 offset:33600
	s_waitcnt lgkmcnt(4)
	v_mfma_f32_16x16x32_bf16 v[140:143], v[230:233], v[16:19], v[140:143]
	v_mfma_f32_16x16x32_bf16 v[136:139], v[230:233], v[64:67], v[136:139]
	s_waitcnt lgkmcnt(3)
	v_mfma_f32_16x16x32_bf16 v[214:217], v[120:123], v[16:19], v[214:217]
	v_mfma_f32_16x16x32_bf16 v[210:213], v[120:123], v[64:67], v[210:213]
	s_waitcnt lgkmcnt(2)
	v_mfma_f32_16x16x32_bf16 v[218:221], v[124:127], v[16:19], v[218:221]
	v_mfma_f32_16x16x32_bf16 v[222:225], v[124:127], v[64:67], v[222:225]
	s_waitcnt lgkmcnt(1)
	v_mfma_f32_16x16x32_bf16 v[148:151], v[128:131], v[20:23], v[148:151]
	v_mfma_f32_16x16x32_bf16 v[144:147], v[128:131], v[68:71], v[144:147]
	s_waitcnt lgkmcnt(0)
	v_mfma_f32_16x16x32_bf16 v[140:143], v[132:135], v[20:23], v[140:143]
	v_mfma_f32_16x16x32_bf16 v[136:139], v[132:135], v[68:71], v[136:139]
	ds_read_b128 v[120:123], v204 offset:40000
	s_nop 1
	ds_read_b128 v[128:131], v204 offset:46400
	ds_read2st64_b32 v[170:171], v184 offset1:3
	ds_read_b32 v205, v184 offset:1536
	ds_read_u16 v226, v194 offset:26880
	ds_read_u16 v227, v194 offset:27280
	ds_read_u16 v228, v194 offset:27680
	ds_read_u16 v229, v194 offset:28080
	ds_read_u16 v230, v194 offset:33280
	ds_read_u16 v231, v194 offset:33680
	ds_read_u16 v232, v194 offset:34080
	ds_read_u16 v233, v194 offset:34480
	ds_read_u16 v234, v194 offset:39680
	ds_read_u16 v235, v194 offset:40080
	ds_read_u16 v236, v194 offset:40480
	ds_read_u16 v237, v194 offset:40880
	ds_read_u16 v238, v194 offset:46080
	ds_read_u16 v239, v194 offset:46480
	ds_read_u16 v240, v194 offset:46880
	ds_read_u16 v241, v194 offset:47280
	s_waitcnt lgkmcnt(15)
	v_mov_b32_e32 v242, 0xbfb8aa3b
	v_mov_b32_e32 v243, 0x4266d4ca
	v_mul_f32_e32 v170, v242, v170
	v_mul_f32_e32 v171, v242, v171
	v_mul_f32_e32 v205, 0x3fb8aa3b, v205
	v_mfma_f32_16x16x32_bf16 v[124:127], v[120:123], v[20:23], v[214:217]
	v_fma_f32 v148, v148, v242, v170
	v_fma_f32 v144, v144, v242, v171
	v_min_f32_e32 v148, v243, v148
	v_min_f32_e32 v144, v243, v144
	v_exp_f32_e32 v148, v148
	v_exp_f32_e32 v144, v144
	v_mfma_f32_16x16x32_bf16 v[120:123], v[120:123], v[68:71], v[210:213]
	v_fma_f32 v145, v145, v242, v171
	v_add_f32_e32 v148, 1.0, v148
	v_add_f32_e32 v144, 1.0, v144
	s_nop 4
	v_mul_f32_e32 v210, v148, v144
	v_rcp_f32_e32 v210, v210
	v_min_f32_e32 v145, v243, v145
	v_mul_f32_e32 v144, v144, v210
	v_mul_f32_e32 v144, v205, v144
	v_exp_f32_e32 v144, v144
	v_mul_f32_e32 v148, v148, v210
	s_waitcnt lgkmcnt(0)
	v_lshlrev_b32_e32 v211, 16, v226
	v_mul_f32_e32 v148, v148, v211
	v_sub_f32_e32 v210, 1.0, v144
	v_add_f32_e32 v144, 1.0, v144
	v_mul_f32_e32 v144, v210, v144
	v_max_f32_e32 v144, 0, v144
	v_sqrt_f32_e32 v144, v144
	v_exp_f32_e32 v145, v145
	v_fma_f32 v140, v140, v242, v170
	v_fma_f32 v136, v136, v242, v171
	v_mul_f32_e32 v144, v148, v144
	v_cvt_pk_bf16_f32 v144, v144, s0
	ds_write_b16 v196, v144
	v_fma_f32 v144, v149, v242, v170
	v_min_f32_e32 v144, v243, v144
	v_exp_f32_e32 v144, v144
	v_cvt_pk_bf16_f32 v148, v210, s0
	v_add_f32_e32 v145, 1.0, v145
	ds_write_b16 v195, v148
	v_add_f32_e32 v144, 1.0, v144
	v_mul_f32_e32 v148, v144, v145
	v_rcp_f32_e32 v148, v148
	v_min_f32_e32 v140, v243, v140
	v_min_f32_e32 v136, v243, v136
	v_mul_f32_e32 v145, v145, v148
	v_mul_f32_e32 v145, v205, v145
	v_exp_f32_e32 v145, v145
	v_mul_f32_e32 v144, v144, v148
	v_lshlrev_b32_e32 v149, 16, v227
	v_mul_f32_e32 v144, v144, v149
	v_sub_f32_e32 v148, 1.0, v145
	v_add_f32_e32 v145, 1.0, v145
	v_mul_f32_e32 v145, v148, v145
	v_max_f32_e32 v145, 0, v145
	v_sqrt_f32_e32 v145, v145
	v_exp_f32_e32 v140, v140
	v_mul_f32_e32 v144, v144, v145
	v_cvt_pk_bf16_f32 v145, v148, s0
	v_cvt_pk_bf16_f32 v144, v144, s0
	ds_write_b16 v195, v145 offset:400
	ds_write_b16 v196, v144 offset:400
	v_fma_f32 v144, v150, v242, v170
	v_fma_f32 v145, v146, v242, v171
	v_min_f32_e32 v144, v243, v144
	v_min_f32_e32 v145, v243, v145
	v_exp_f32_e32 v144, v144
	v_exp_f32_e32 v145, v145
	v_exp_f32_e32 v136, v136
	v_add_f32_e32 v144, 1.0, v144
	v_add_f32_e32 v145, 1.0, v145
	v_mul_f32_e32 v146, v144, v145
	v_rcp_f32_e32 v146, v146
	v_lshlrev_b32_e32 v148, 16, v228
	v_add_f32_e32 v140, 1.0, v140
	v_add_f32_e32 v136, 1.0, v136
	v_mul_f32_e32 v145, v145, v146
	v_mul_f32_e32 v145, v205, v145
; #define LAS __attribute__((address_space(3)))
; DI unsigned pk2(float a, float b) { f32x2 v = {a, b}; bf2_t r = __builtin_convertvector(v, bf2_t); return __builtin_bit_cast(unsigned, r); }
; DI void phase_rglru(const Params& p, unsigned char* shm) {
;     ...
;                     const float ba = gb[ch], bx = gb[192 + ch], sp = gb[384 + ch];
; #pragma unroll
;                     for (int mt = 0; mt < 4; ++mt)
; #pragma unroll
;                         for (int j = 0; j < 4; ++j) {
;                             const int t = 16 * mt + 4 * fq + j;
;                             const float ea = 1.f + __expf(fminf(-(acc[mt][0][j] + ba), 40.f)), ex = 1.f + __expf(fminf(-(acc[mt][1][j] + bx), 40.f));
;                             const float inv = __builtin_amdgcn_rcpf(ea * ex);
;                             const float r = inv * ex, ig = inv * ea;
;                             const float av = __expf(r * sp), om = 1.f - av;
;                             const float xcv = __uint_as_float((unsigned)*(const LAS bf16_t*)(lds + XC + t * TR + ch * 2) << 16);
;                             const float bt = __builtin_amdgcn_sqrtf(fmaxf(om * (1.f + av), 0.f)) * (ig * xcv);
;                             *(LAS bf16_t*)(lds + LAo + t * TR + ch * 2) = (bf16_t)(pk2(om, 0.f) & 0xffffu);
;                             *(LAS bf16_t*)(lds + BTo + t * TR + ch * 2) = (bf16_t)(pk2(bt, 0.f) & 0xffffu);
;                         }
	v_exp_f32_e32 v145, v145
	v_mul_f32_e32 v144, v144, v146
	v_mul_f32_e32 v144, v144, v148
	v_fma_f32 v137, v137, v242, v171
	v_sub_f32_e32 v146, 1.0, v145
	v_add_f32_e32 v145, 1.0, v145
	v_mul_f32_e32 v145, v146, v145
	v_max_f32_e32 v145, 0, v145
	v_sqrt_f32_e32 v145, v145
	v_min_f32_e32 v137, v243, v137
	v_exp_f32_e32 v137, v137
	v_mul_f32_e32 v144, v144, v145
	v_cvt_pk_bf16_f32 v145, v146, s0
	v_cvt_pk_bf16_f32 v144, v144, s0
	ds_write_b16 v195, v145 offset:800
	ds_write_b16 v196, v144 offset:800
	v_fma_f32 v144, v151, v242, v170
	v_fma_f32 v145, v147, v242, v171
	v_min_f32_e32 v144, v243, v144
	v_min_f32_e32 v145, v243, v145
	v_exp_f32_e32 v144, v144
	v_exp_f32_e32 v145, v145
	v_add_f32_e32 v137, 1.0, v137
	v_add_f32_e32 v144, 1.0, v144
	v_add_f32_e32 v145, 1.0, v145
	v_mul_f32_e32 v146, v144, v145
	v_rcp_f32_e32 v146, v146
	v_lshlrev_b32_e32 v147, 16, v229
	v_fma_f32 v124, v124, v242, v170
	v_fma_f32 v120, v120, v242, v171
	v_mul_f32_e32 v145, v145, v146
	v_mul_f32_e32 v145, v205, v145
	v_exp_f32_e32 v145, v145
	v_mul_f32_e32 v144, v144, v146
	v_mul_f32_e32 v144, v144, v147
	v_min_f32_e32 v124, v243, v124
	v_sub_f32_e32 v146, 1.0, v145
	v_add_f32_e32 v145, 1.0, v145
	v_mul_f32_e32 v145, v146, v145
	v_max_f32_e32 v145, 0, v145
	v_sqrt_f32_e32 v145, v145
	v_min_f32_e32 v120, v243, v120
	v_mul_f32_e32 v144, v144, v145
	v_cvt_pk_bf16_f32 v144, v144, s0
	ds_write_b16 v196, v144 offset:1200
	v_mul_f32_e32 v144, v140, v136
	v_rcp_f32_e32 v144, v144
	v_cvt_pk_bf16_f32 v145, v146, s0
	ds_write_b16 v195, v145 offset:1200
	v_exp_f32_e32 v124, v124
	v_mul_f32_e32 v145, v136, v144
	v_mul_f32_e32 v136, v140, v144
	v_mul_f32_e32 v140, v205, v145
	v_exp_f32_e32 v144, v140
	v_exp_f32_e32 v120, v120
	v_add_f32_e32 v124, 1.0, v124
	v_sub_f32_e32 v140, 1.0, v144
	v_add_f32_e32 v144, 1.0, v144
	v_mul_f32_e32 v144, v140, v144
	v_max_f32_e32 v144, 0, v144
	v_sqrt_f32_e32 v144, v144
	v_lshlrev_b32_e32 v145, 16, v230
	v_mul_f32_e32 v136, v136, v145
	v_cvt_pk_bf16_f32 v140, v140, s0
	v_mul_f32_e32 v136, v144, v136
	v_cvt_pk_bf16_f32 v136, v136, s0
	ds_write_b16 v196, v136 offset:6400
	v_fma_f32 v136, v141, v242, v170
	v_min_f32_e32 v136, v243, v136
	v_exp_f32_e32 v136, v136
	ds_write_b16 v195, v140 offset:6400
	v_add_f32_e32 v120, 1.0, v120
	v_add_f32_e32 v136, 1.0, v136
	v_mul_f32_e32 v140, v136, v137
	v_rcp_f32_e32 v140, v140
	v_lshlrev_b32_e32 v141, 16, v231
	v_fma_f32 v121, v121, v242, v171
	v_min_f32_e32 v121, v243, v121
	v_mul_f32_e32 v137, v137, v140
	v_mul_f32_e32 v137, v205, v137
	v_exp_f32_e32 v137, v137
	v_mul_f32_e32 v136, v136, v140
	v_mul_f32_e32 v136, v136, v141
	v_sub_f32_e32 v140, 1.0, v137
	v_add_f32_e32 v137, 1.0, v137
	v_mul_f32_e32 v137, v140, v137
	v_max_f32_e32 v137, 0, v137
	v_sqrt_f32_e32 v137, v137
	v_exp_f32_e32 v121, v121
	v_mfma_f32_16x16x32_bf16 v[132:135], v[128:131], v[20:23], v[218:221]
	v_mul_f32_e32 v136, v137, v136
	v_cvt_pk_bf16_f32 v137, v140, s0
	v_cvt_pk_bf16_f32 v136, v136, s0
	ds_write_b16 v195, v137 offset:6800
	ds_write_b16 v196, v136 offset:6800
	v_fma_f32 v136, v142, v242, v170
	v_fma_f32 v137, v138, v242, v171
	v_min_f32_e32 v136, v243, v136
	v_min_f32_e32 v137, v243, v137
	v_exp_f32_e32 v136, v136
	v_exp_f32_e32 v137, v137
	v_add_f32_e32 v121, 1.0, v121
	v_add_f32_e32 v136, 1.0, v136
	v_add_f32_e32 v137, 1.0, v137
	v_mul_f32_e32 v138, v136, v137
	v_rcp_f32_e32 v138, v138
	v_lshlrev_b32_e32 v140, 16, v232
	v_mfma_f32_16x16x32_bf16 v[128:131], v[128:131], v[68:71], v[222:225]
	v_mul_f32_e32 v137, v137, v138
	v_mul_f32_e32 v137, v205, v137
	v_exp_f32_e32 v137, v137
	v_mul_f32_e32 v136, v136, v138
	v_mul_f32_e32 v136, v136, v140
	v_sub_f32_e32 v138, 1.0, v137
	v_add_f32_e32 v137, 1.0, v137
	v_mul_f32_e32 v137, v138, v137
	v_max_f32_e32 v137, 0, v137
	v_sqrt_f32_e32 v137, v137
	s_nop 0
	v_mul_f32_e32 v136, v137, v136
	v_cvt_pk_bf16_f32 v137, v138, s0
	v_cvt_pk_bf16_f32 v136, v136, s0
	ds_write_b16 v195, v137 offset:7200
	ds_write_b16 v196, v136 offset:7200
	v_fma_f32 v136, v143, v242, v170
	v_fma_f32 v137, v139, v242, v171
	v_min_f32_e32 v136, v243, v136
	v_min_f32_e32 v137, v243, v137
	v_exp_f32_e32 v136, v136
	v_exp_f32_e32 v137, v137
	v_add_f32_e32 v136, 1.0, v136
	v_add_f32_e32 v137, 1.0, v137
	v_mul_f32_e32 v138, v136, v137
	v_rcp_f32_e32 v138, v138
	v_lshlrev_b32_e32 v139, 16, v233
	v_mul_f32_e32 v137, v137, v138
	v_mul_f32_e32 v137, v205, v137
	v_exp_f32_e32 v137, v137
	v_mul_f32_e32 v136, v136, v138
	v_mul_f32_e32 v136, v136, v139
	v_sub_f32_e32 v138, 1.0, v137
	v_add_f32_e32 v137, 1.0, v137
	v_mul_f32_e32 v137, v138, v137
	v_max_f32_e32 v137, 0, v137
	v_sqrt_f32_e32 v137, v137
	s_nop 0
	v_mul_f32_e32 v136, v137, v136
	v_cvt_pk_bf16_f32 v136, v136, s0
	ds_write_b16 v196, v136 offset:7600
	v_mul_f32_e32 v136, v124, v120
	v_rcp_f32_e32 v136, v136
	v_cvt_pk_bf16_f32 v137, v138, s0
	ds_write_b16 v195, v137 offset:7600
	v_mul_f32_e32 v120, v120, v136
	v_mul_f32_e32 v120, v205, v120
	v_exp_f32_e32 v120, v120
	v_mul_f32_e32 v124, v124, v136
	v_lshlrev_b32_e32 v137, 16, v234
	v_mul_f32_e32 v124, v124, v137
	v_sub_f32_e32 v136, 1.0, v120
	v_add_f32_e32 v120, 1.0, v120
	v_mul_f32_e32 v120, v136, v120
	v_max_f32_e32 v120, 0, v120
	v_sqrt_f32_e32 v120, v120
	s_nop 0
	v_mul_f32_e32 v120, v120, v124
	v_cvt_pk_bf16_f32 v120, v120, s0
	ds_write_b16 v196, v120 offset:12800
	v_fma_f32 v120, v125, v242, v170
	v_min_f32_e32 v120, v243, v120
	v_exp_f32_e32 v120, v120
	v_cvt_pk_bf16_f32 v124, v136, s0
	ds_write_b16 v195, v124 offset:12800
	v_add_f32_e32 v120, 1.0, v120
	v_mul_f32_e32 v124, v120, v121
	v_rcp_f32_e32 v124, v124
	v_lshlrev_b32_e32 v125, 16, v235
	v_mul_f32_e32 v121, v121, v124
	v_mul_f32_e32 v121, v205, v121
; #define LAS __attribute__((address_space(3)))
; DI unsigned pk2(float a, float b) { f32x2 v = {a, b}; bf2_t r = __builtin_convertvector(v, bf2_t); return __builtin_bit_cast(unsigned, r); }
; DI void phase_rglru(const Params& p, unsigned char* shm) {
;     ...
;                     const float ba = gb[ch], bx = gb[192 + ch], sp = gb[384 + ch];
; #pragma unroll
;                     for (int mt = 0; mt < 4; ++mt)
; #pragma unroll
;                         for (int j = 0; j < 4; ++j) {
;                             const int t = 16 * mt + 4 * fq + j;
;                             const float ea = 1.f + __expf(fminf(-(acc[mt][0][j] + ba), 40.f)), ex = 1.f + __expf(fminf(-(acc[mt][1][j] + bx), 40.f));
;                             const float inv = __builtin_amdgcn_rcpf(ea * ex);
;                             const float r = inv * ex, ig = inv * ea;
;                             const float av = __expf(r * sp), om = 1.f - av;
;                             const float xcv = __uint_as_float((unsigned)*(const LAS bf16_t*)(lds + XC + t * TR + ch * 2) << 16);
;                             const float bt = __builtin_amdgcn_sqrtf(fmaxf(om * (1.f + av), 0.f)) * (ig * xcv);
;                             *(LAS bf16_t*)(lds + LAo + t * TR + ch * 2) = (bf16_t)(pk2(om, 0.f) & 0xffffu);
;                             *(LAS bf16_t*)(lds + BTo + t * TR + ch * 2) = (bf16_t)(pk2(bt, 0.f) & 0xffffu);
;                         }
	v_exp_f32_e32 v121, v121
	v_mul_f32_e32 v120, v120, v124
	v_mul_f32_e32 v120, v120, v125
	v_sub_f32_e32 v124, 1.0, v121
	v_add_f32_e32 v121, 1.0, v121
	v_mul_f32_e32 v121, v124, v121
	v_max_f32_e32 v121, 0, v121
	v_sqrt_f32_e32 v121, v121
	s_nop 0
	v_mul_f32_e32 v120, v121, v120
	v_cvt_pk_bf16_f32 v121, v124, s0
	v_cvt_pk_bf16_f32 v120, v120, s0
	ds_write_b16 v195, v121 offset:13200
	ds_write_b16 v196, v120 offset:13200
	v_fma_f32 v120, v126, v242, v170
	v_fma_f32 v121, v122, v242, v171
	v_min_f32_e32 v120, v243, v120
	v_min_f32_e32 v121, v243, v121
	v_exp_f32_e32 v120, v120
	v_exp_f32_e32 v121, v121
	v_add_f32_e32 v120, 1.0, v120
	v_add_f32_e32 v121, 1.0, v121
	v_mul_f32_e32 v122, v120, v121
	v_rcp_f32_e32 v122, v122
	v_lshlrev_b32_e32 v124, 16, v236
	v_mul_f32_e32 v121, v121, v122
	v_mul_f32_e32 v121, v205, v121
	v_exp_f32_e32 v121, v121
	v_mul_f32_e32 v120, v120, v122
	v_mul_f32_e32 v120, v120, v124
	v_sub_f32_e32 v122, 1.0, v121
	v_add_f32_e32 v121, 1.0, v121
	v_mul_f32_e32 v121, v122, v121
	v_max_f32_e32 v121, 0, v121
	v_sqrt_f32_e32 v121, v121
	s_nop 0
	v_mul_f32_e32 v120, v121, v120
	v_cvt_pk_bf16_f32 v121, v122, s0
	v_cvt_pk_bf16_f32 v120, v120, s0
	ds_write_b16 v195, v121 offset:13600
	ds_write_b16 v196, v120 offset:13600
	v_fma_f32 v120, v127, v242, v170
	v_fma_f32 v121, v123, v242, v171
	v_min_f32_e32 v120, v243, v120
	v_min_f32_e32 v121, v243, v121
	v_exp_f32_e32 v120, v120
	v_exp_f32_e32 v121, v121
	v_add_f32_e32 v120, 1.0, v120
	v_add_f32_e32 v121, 1.0, v121
	v_mul_f32_e32 v122, v120, v121
	v_rcp_f32_e32 v122, v122
	v_lshlrev_b32_e32 v123, 16, v237
	v_mul_f32_e32 v121, v121, v122
	v_mul_f32_e32 v121, v205, v121
	v_exp_f32_e32 v121, v121
	v_mul_f32_e32 v120, v120, v122
	v_mul_f32_e32 v120, v120, v123
	v_sub_f32_e32 v122, 1.0, v121
	v_add_f32_e32 v121, 1.0, v121
	v_mul_f32_e32 v121, v122, v121
	v_max_f32_e32 v121, 0, v121
	v_sqrt_f32_e32 v121, v121
	v_lshlrev_b32_e32 v123, 16, v238
	v_mul_f32_e32 v120, v121, v120
	v_cvt_pk_bf16_f32 v121, v122, s0
	v_cvt_pk_bf16_f32 v120, v120, s0
	ds_write_b16 v195, v121 offset:14000
	ds_write_b16 v196, v120 offset:14000
	v_fma_f32 v120, v132, v242, v170
	v_fma_f32 v121, v128, v242, v171
	v_min_f32_e32 v120, v243, v120
	v_min_f32_e32 v121, v243, v121
	v_exp_f32_e32 v120, v120
	v_exp_f32_e32 v121, v121
	v_add_f32_e32 v120, 1.0, v120
	v_add_f32_e32 v121, 1.0, v121
	v_mul_f32_e32 v122, v120, v121
	v_rcp_f32_e32 v122, v122
	s_nop 0
	v_mul_f32_e32 v121, v121, v122
	v_mul_f32_e32 v121, v205, v121
	v_exp_f32_e32 v121, v121
	v_mul_f32_e32 v120, v120, v122
	v_mul_f32_e32 v120, v120, v123
	v_sub_f32_e32 v122, 1.0, v121
	v_add_f32_e32 v121, 1.0, v121
	v_mul_f32_e32 v121, v122, v121
	v_max_f32_e32 v121, 0, v121
	v_sqrt_f32_e32 v121, v121
	v_lshlrev_b32_e32 v123, 16, v239
	v_mul_f32_e32 v120, v121, v120
	v_cvt_pk_bf16_f32 v121, v122, s0
	v_cvt_pk_bf16_f32 v120, v120, s0
	ds_write_b16 v195, v121 offset:19200
	ds_write_b16 v196, v120 offset:19200
	v_fma_f32 v120, v133, v242, v170
	v_fma_f32 v121, v129, v242, v171
	v_min_f32_e32 v120, v243, v120
	v_min_f32_e32 v121, v243, v121
	v_exp_f32_e32 v120, v120
	v_exp_f32_e32 v121, v121
	v_add_f32_e32 v120, 1.0, v120
	v_add_f32_e32 v121, 1.0, v121
	v_mul_f32_e32 v122, v120, v121
	v_rcp_f32_e32 v122, v122
	s_nop 0
	v_mul_f32_e32 v121, v121, v122
	v_mul_f32_e32 v121, v205, v121
	v_exp_f32_e32 v121, v121
	v_mul_f32_e32 v120, v120, v122
	v_mul_f32_e32 v120, v120, v123
	v_sub_f32_e32 v122, 1.0, v121
	v_add_f32_e32 v121, 1.0, v121
	v_mul_f32_e32 v121, v122, v121
	v_max_f32_e32 v121, 0, v121
	v_sqrt_f32_e32 v121, v121
	v_lshlrev_b32_e32 v123, 16, v240
	v_mul_f32_e32 v120, v121, v120
	v_cvt_pk_bf16_f32 v121, v122, s0
	v_cvt_pk_bf16_f32 v120, v120, s0
	ds_write_b16 v195, v121 offset:19600
	ds_write_b16 v196, v120 offset:19600
	v_fma_f32 v120, v134, v242, v170
	v_fma_f32 v121, v130, v242, v171
	v_min_f32_e32 v120, v243, v120
	v_min_f32_e32 v121, v243, v121
	v_exp_f32_e32 v120, v120
	v_exp_f32_e32 v121, v121
	v_add_f32_e32 v120, 1.0, v120
	v_add_f32_e32 v121, 1.0, v121
	v_mul_f32_e32 v122, v120, v121
	v_rcp_f32_e32 v122, v122
	s_nop 0
	v_mul_f32_e32 v121, v121, v122
	v_mul_f32_e32 v121, v205, v121
	v_exp_f32_e32 v121, v121
	v_mul_f32_e32 v120, v120, v122
	v_mul_f32_e32 v120, v120, v123
	v_sub_f32_e32 v122, 1.0, v121
	v_add_f32_e32 v121, 1.0, v121
	v_mul_f32_e32 v121, v122, v121
	v_max_f32_e32 v121, 0, v121
	v_sqrt_f32_e32 v121, v121
	v_lshlrev_b32_e32 v123, 16, v241
	v_mul_f32_e32 v120, v121, v120
	v_cvt_pk_bf16_f32 v121, v122, s0
	v_cvt_pk_bf16_f32 v120, v120, s0
	ds_write_b16 v195, v121 offset:20000
	ds_write_b16 v196, v120 offset:20000
	v_fma_f32 v120, v135, v242, v170
	v_fma_f32 v121, v131, v242, v171
	v_min_f32_e32 v120, v243, v120
	v_min_f32_e32 v121, v243, v121
	v_exp_f32_e32 v120, v120
	v_exp_f32_e32 v121, v121
	v_add_f32_e32 v120, 1.0, v120
	v_add_f32_e32 v121, 1.0, v121
	v_mul_f32_e32 v122, v120, v121
	v_rcp_f32_e32 v122, v122
	s_nop 0
	v_mul_f32_e32 v121, v121, v122
	v_mul_f32_e32 v121, v205, v121
	v_mul_f32_e32 v120, v120, v122
	v_exp_f32_e32 v122, v121
	v_mul_f32_e32 v120, v120, v123
	v_sub_f32_e32 v121, 1.0, v122
	v_add_f32_e32 v122, 1.0, v122
	v_mul_f32_e32 v122, v121, v122
	v_max_f32_e32 v122, 0, v122
	v_sqrt_f32_e32 v122, v122
	v_cvt_pk_bf16_f32 v121, v121, s0
	ds_write_b16 v195, v121 offset:20400
	v_mul_f32_e32 v120, v122, v120
	v_cvt_pk_bf16_f32 v120, v120, s0
	ds_write_b16 v196, v120 offset:20400
	s_andn2_b64 vcc, exec, s[12:13]
	s_cbranch_vccnz .Lgates_b
; #define LAS __attribute__((address_space(3)))
; DI unsigned pk2(float a, float b) { f32x2 v = {a, b}; bf2_t r = __builtin_convertvector(v, bf2_t); return __builtin_bit_cast(unsigned, r); }
; DI void phase_rglru(const Params& p, unsigned char* shm) {
;     ...
;                     for (int kk = 0; kk < 6; ++kk)
; #pragma unroll
;                         for (int mt = 0; mt < 4; ++mt) {
;                             const bf16x8 af = *(const LAS bf16x8*)(lds + XC + (16 * mt + fr) * TR + (32 * kk + 8 * fq) * 2);
;                             acc[mt][0] = __builtin_amdgcn_mfma_f32_16x16x32_bf16(af, Bf[u][kk], acc[mt][0], 0, 0, 0);
;                             acc[mt][1] = __builtin_amdgcn_mfma_f32_16x16x32_bf16(af, Bf[2 + u][kk], acc[mt][1], 0, 0, 0);
;                         }
;                     const int ch = chb + 16 * u + fr;
;                     const float ba = gb[ch], bx = gb[192 + ch], sp = gb[384 + ch];
; #pragma unroll
;                     for (int mt = 0; mt < 4; ++mt)
; #pragma unroll
;                         for (int j = 0; j < 4; ++j) {
;                             const int t = 16 * mt + 4 * fq + j;
;                             const float ea = 1.f + __expf(fminf(-(acc[mt][0][j] + ba), 40.f)), ex = 1.f + __expf(fminf(-(acc[mt][1][j] + bx), 40.f));
;                             const float inv = __builtin_amdgcn_rcpf(ea * ex);
;                             const float r = inv * ex, ig = inv * ea;
;                             const float av = __expf(r * sp), om = 1.f - av;
;                             const float xcv = __uint_as_float((unsigned)*(const LAS bf16_t*)(lds + XC + t * TR + ch * 2) << 16);
;                             const float bt = __builtin_amdgcn_sqrtf(fmaxf(om * (1.f + av), 0.f)) * (ig * xcv);
;                             *(LAS bf16_t*)(lds + LAo + t * TR + ch * 2) = (bf16_t)(pk2(om, 0.f) & 0xffffu);
;                             *(LAS bf16_t*)(lds + BTo + t * TR + ch * 2) = (bf16_t)(pk2(bt, 0.f) & 0xffffu);
;                         }
	ds_read_b128 v[120:123], v204 offset:26880
	ds_read_b128 v[124:127], v204 offset:33280
	ds_read_b128 v[128:131], v204 offset:26944
	ds_read_b128 v[132:135], v204 offset:33344
	ds_read_b128 v[226:229], v204 offset:27008
	s_waitcnt lgkmcnt(4)
	v_mfma_f32_16x16x32_bf16 v[148:151], v[120:123], v[24:27], 0
	v_mfma_f32_16x16x32_bf16 v[144:147], v[120:123], v[72:75], 0
	ds_read_b128 v[230:233], v204 offset:33408
	s_waitcnt lgkmcnt(4)
	v_mfma_f32_16x16x32_bf16 v[140:143], v[124:127], v[24:27], 0
	v_mfma_f32_16x16x32_bf16 v[136:139], v[124:127], v[72:75], 0
	ds_read_b128 v[120:123], v204 offset:27072
	s_waitcnt lgkmcnt(4)
	v_mfma_f32_16x16x32_bf16 v[148:151], v[128:131], v[28:31], v[148:151]
	v_mfma_f32_16x16x32_bf16 v[144:147], v[128:131], v[76:79], v[144:147]
	ds_read_b128 v[124:127], v204 offset:33472
	s_waitcnt lgkmcnt(4)
	v_mfma_f32_16x16x32_bf16 v[140:143], v[132:135], v[28:31], v[140:143]
	v_mfma_f32_16x16x32_bf16 v[136:139], v[132:135], v[76:79], v[136:139]
	ds_read_b128 v[128:131], v204 offset:27136
	s_waitcnt lgkmcnt(4)
	v_mfma_f32_16x16x32_bf16 v[148:151], v[226:229], v[32:35], v[148:151]
	v_mfma_f32_16x16x32_bf16 v[144:147], v[226:229], v[80:83], v[144:147]
	ds_read_b128 v[132:135], v204 offset:33536
	s_waitcnt lgkmcnt(4)
	v_mfma_f32_16x16x32_bf16 v[140:143], v[230:233], v[32:35], v[140:143]
	v_mfma_f32_16x16x32_bf16 v[136:139], v[230:233], v[80:83], v[136:139]
	ds_read_b128 v[226:229], v204 offset:27200
	s_waitcnt lgkmcnt(4)
	v_mfma_f32_16x16x32_bf16 v[148:151], v[120:123], v[36:39], v[148:151]
	v_mfma_f32_16x16x32_bf16 v[144:147], v[120:123], v[84:87], v[144:147]
	ds_read_b128 v[230:233], v204 offset:33600
	s_waitcnt lgkmcnt(4)
	v_mfma_f32_16x16x32_bf16 v[140:143], v[124:127], v[36:39], v[140:143]
	v_mfma_f32_16x16x32_bf16 v[136:139], v[124:127], v[84:87], v[136:139]
	s_waitcnt lgkmcnt(3)
	v_mfma_f32_16x16x32_bf16 v[148:151], v[128:131], v[40:43], v[148:151]
	v_mfma_f32_16x16x32_bf16 v[144:147], v[128:131], v[88:91], v[144:147]
	s_waitcnt lgkmcnt(2)
	v_mfma_f32_16x16x32_bf16 v[140:143], v[132:135], v[40:43], v[140:143]
	v_mfma_f32_16x16x32_bf16 v[136:139], v[132:135], v[88:91], v[136:139]
	s_waitcnt lgkmcnt(1)
	v_mfma_f32_16x16x32_bf16 v[148:151], v[226:229], v[44:47], v[148:151]
	v_mfma_f32_16x16x32_bf16 v[144:147], v[226:229], v[92:95], v[144:147]
	s_waitcnt lgkmcnt(0)
	v_mfma_f32_16x16x32_bf16 v[140:143], v[230:233], v[44:47], v[140:143]
	v_mfma_f32_16x16x32_bf16 v[136:139], v[230:233], v[92:95], v[136:139]
	s_nop 1
	ds_read2st64_b32 v[170:171], v185 offset1:3
	ds_read_b32 v205, v185 offset:1536
	ds_read_u16 v226, v197 offset:26880
	ds_read_u16 v227, v197 offset:27280
	ds_read_u16 v228, v197 offset:27680
	ds_read_u16 v229, v197 offset:28080
	ds_read_u16 v230, v197 offset:33280
	ds_read_u16 v231, v197 offset:33680
	ds_read_u16 v232, v197 offset:34080
	ds_read_u16 v233, v197 offset:34480
	ds_read_u16 v234, v197 offset:39680
	ds_read_u16 v235, v197 offset:40080
	ds_read_u16 v236, v197 offset:40480
	ds_read_u16 v237, v197 offset:40880
	ds_read_u16 v238, v197 offset:46080
	ds_read_u16 v239, v197 offset:46480
	ds_read_u16 v240, v197 offset:46880
	ds_read_u16 v241, v197 offset:47280
	s_waitcnt lgkmcnt(15)
	v_mov_b32_e32 v242, 0xbfb8aa3b
	v_mov_b32_e32 v243, 0x4266d4ca
	v_mul_f32_e32 v170, v242, v170
	v_mul_f32_e32 v171, v242, v171
	v_mul_f32_e32 v205, 0x3fb8aa3b, v205
	v_fma_f32 v148, v148, v242, v170
	v_fma_f32 v144, v144, v242, v171
	v_min_f32_e32 v148, v243, v148
	v_min_f32_e32 v144, v243, v144
	v_exp_f32_e32 v148, v148
	v_exp_f32_e32 v144, v144
	v_fma_f32 v145, v145, v242, v171
	v_add_f32_e32 v148, 1.0, v148
	v_add_f32_e32 v144, 1.0, v144
	v_mul_f32_e32 v210, v148, v144
	v_rcp_f32_e32 v210, v210
	v_min_f32_e32 v145, v243, v145
	v_mul_f32_e32 v144, v144, v210
	v_mul_f32_e32 v144, v205, v144
	v_exp_f32_e32 v144, v144
	v_mul_f32_e32 v148, v148, v210
	s_waitcnt lgkmcnt(0)
	v_lshlrev_b32_e32 v211, 16, v226
	v_mul_f32_e32 v148, v148, v211
	v_sub_f32_e32 v210, 1.0, v144
	v_add_f32_e32 v144, 1.0, v144
	v_mul_f32_e32 v144, v210, v144
	v_max_f32_e32 v144, 0, v144
	v_sqrt_f32_e32 v144, v144
	v_exp_f32_e32 v145, v145
	v_fma_f32 v140, v140, v242, v170
	v_fma_f32 v136, v136, v242, v171
	v_mul_f32_e32 v144, v148, v144
	v_cvt_pk_bf16_f32 v144, v144, s0
	ds_write_b16 v199, v144
	v_fma_f32 v144, v149, v242, v170
	v_min_f32_e32 v144, v243, v144
	v_exp_f32_e32 v144, v144
	v_cvt_pk_bf16_f32 v148, v210, s0
	v_add_f32_e32 v145, 1.0, v145
	ds_write_b16 v198, v148
	v_add_f32_e32 v144, 1.0, v144
	v_mul_f32_e32 v148, v144, v145
	v_rcp_f32_e32 v148, v148
	v_min_f32_e32 v140, v243, v140
	v_min_f32_e32 v136, v243, v136
	v_mul_f32_e32 v145, v145, v148
	v_mul_f32_e32 v145, v205, v145
	v_exp_f32_e32 v145, v145
	v_mul_f32_e32 v144, v144, v148
	v_lshlrev_b32_e32 v149, 16, v227
	v_mul_f32_e32 v144, v144, v149
	v_sub_f32_e32 v148, 1.0, v145
	v_add_f32_e32 v145, 1.0, v145
	v_mul_f32_e32 v145, v148, v145
	v_max_f32_e32 v145, 0, v145
	v_sqrt_f32_e32 v145, v145
	v_exp_f32_e32 v140, v140
	v_mul_f32_e32 v144, v144, v145
	v_cvt_pk_bf16_f32 v145, v148, s0
	v_cvt_pk_bf16_f32 v144, v144, s0
	ds_write_b16 v198, v145 offset:400
	ds_write_b16 v199, v144 offset:400
	v_fma_f32 v144, v150, v242, v170
	v_fma_f32 v145, v146, v242, v171
	v_min_f32_e32 v144, v243, v144
	v_min_f32_e32 v145, v243, v145
	v_exp_f32_e32 v144, v144
	v_exp_f32_e32 v145, v145
	v_exp_f32_e32 v136, v136
	v_add_f32_e32 v144, 1.0, v144
	v_add_f32_e32 v145, 1.0, v145
	v_mul_f32_e32 v146, v144, v145
	v_rcp_f32_e32 v146, v146
	v_lshlrev_b32_e32 v148, 16, v228
	v_add_f32_e32 v140, 1.0, v140
	v_add_f32_e32 v136, 1.0, v136
	v_mul_f32_e32 v145, v145, v146
	v_mul_f32_e32 v145, v205, v145
	v_exp_f32_e32 v145, v145
; #define LAS __attribute__((address_space(3)))
; DI unsigned pk2(float a, float b) { f32x2 v = {a, b}; bf2_t r = __builtin_convertvector(v, bf2_t); return __builtin_bit_cast(unsigned, r); }
; DI void phase_rglru(const Params& p, unsigned char* shm) {
;     ...
;                     const float ba = gb[ch], bx = gb[192 + ch], sp = gb[384 + ch];
; #pragma unroll
;                     for (int mt = 0; mt < 4; ++mt)
; #pragma unroll
;                         for (int j = 0; j < 4; ++j) {
;                             const int t = 16 * mt + 4 * fq + j;
;                             const float ea = 1.f + __expf(fminf(-(acc[mt][0][j] + ba), 40.f)), ex = 1.f + __expf(fminf(-(acc[mt][1][j] + bx), 40.f));
;                             const float inv = __builtin_amdgcn_rcpf(ea * ex);
;                             const float r = inv * ex, ig = inv * ea;
;                             const float av = __expf(r * sp), om = 1.f - av;
;                             const float xcv = __uint_as_float((unsigned)*(const LAS bf16_t*)(lds + XC + t * TR + ch * 2) << 16);
;                             const float bt = __builtin_amdgcn_sqrtf(fmaxf(om * (1.f + av), 0.f)) * (ig * xcv);
;                             *(LAS bf16_t*)(lds + LAo + t * TR + ch * 2) = (bf16_t)(pk2(om, 0.f) & 0xffffu);
;                             *(LAS bf16_t*)(lds + BTo + t * TR + ch * 2) = (bf16_t)(pk2(bt, 0.f) & 0xffffu);
;                         }
	v_mul_f32_e32 v144, v144, v146
	v_mul_f32_e32 v144, v144, v148
	v_fma_f32 v137, v137, v242, v171
	v_sub_f32_e32 v146, 1.0, v145
	v_add_f32_e32 v145, 1.0, v145
	v_mul_f32_e32 v145, v146, v145
	v_max_f32_e32 v145, 0, v145
	v_sqrt_f32_e32 v145, v145
	v_min_f32_e32 v137, v243, v137
	v_exp_f32_e32 v137, v137
	v_mul_f32_e32 v144, v144, v145
	v_cvt_pk_bf16_f32 v145, v146, s0
	v_cvt_pk_bf16_f32 v144, v144, s0
	ds_write_b16 v198, v145 offset:800
	ds_write_b16 v199, v144 offset:800
	v_fma_f32 v144, v151, v242, v170
	v_fma_f32 v145, v147, v242, v171
	v_min_f32_e32 v144, v243, v144
	v_min_f32_e32 v145, v243, v145
	v_exp_f32_e32 v144, v144
	v_exp_f32_e32 v145, v145
	v_add_f32_e32 v137, 1.0, v137
	v_add_f32_e32 v144, 1.0, v144
	v_add_f32_e32 v145, 1.0, v145
	v_mul_f32_e32 v146, v144, v145
	v_rcp_f32_e32 v146, v146
	v_lshlrev_b32_e32 v147, 16, v229
	v_mul_f32_e32 v145, v145, v146
	v_mul_f32_e32 v145, v205, v145
	v_exp_f32_e32 v145, v145
	v_mul_f32_e32 v144, v144, v146
	v_mul_f32_e32 v144, v144, v147
	v_sub_f32_e32 v146, 1.0, v145
	v_add_f32_e32 v145, 1.0, v145
	v_mul_f32_e32 v145, v146, v145
	v_max_f32_e32 v145, 0, v145
	v_sqrt_f32_e32 v145, v145
	s_nop 0
	v_mul_f32_e32 v144, v144, v145
	v_cvt_pk_bf16_f32 v144, v144, s0
	ds_write_b16 v199, v144 offset:1200
	v_mul_f32_e32 v144, v140, v136
	v_rcp_f32_e32 v144, v144
	v_cvt_pk_bf16_f32 v145, v146, s0
	ds_write_b16 v198, v145 offset:1200
	v_mul_f32_e32 v145, v136, v144
	v_mul_f32_e32 v136, v140, v144
	v_mul_f32_e32 v140, v205, v145
	v_exp_f32_e32 v144, v140
	s_nop 0
	v_sub_f32_e32 v140, 1.0, v144
	v_add_f32_e32 v144, 1.0, v144
	v_mul_f32_e32 v144, v140, v144
	v_max_f32_e32 v144, 0, v144
	v_sqrt_f32_e32 v144, v144
	v_lshlrev_b32_e32 v145, 16, v230
	v_mul_f32_e32 v136, v136, v145
	v_cvt_pk_bf16_f32 v140, v140, s0
	v_mul_f32_e32 v136, v144, v136
	v_cvt_pk_bf16_f32 v136, v136, s0
	ds_write_b16 v199, v136 offset:6400
	v_fma_f32 v136, v141, v242, v170
	v_min_f32_e32 v136, v243, v136
	v_exp_f32_e32 v136, v136
	ds_write_b16 v198, v140 offset:6400
	v_add_f32_e32 v136, 1.0, v136
	v_mul_f32_e32 v140, v136, v137
	v_rcp_f32_e32 v140, v140
	v_lshlrev_b32_e32 v141, 16, v231
	v_mul_f32_e32 v137, v137, v140
	v_mul_f32_e32 v137, v205, v137
	v_exp_f32_e32 v137, v137
	v_mul_f32_e32 v136, v136, v140
	v_mul_f32_e32 v136, v136, v141
	v_sub_f32_e32 v140, 1.0, v137
	v_add_f32_e32 v137, 1.0, v137
	v_mul_f32_e32 v137, v140, v137
	v_max_f32_e32 v137, 0, v137
	v_sqrt_f32_e32 v137, v137
	s_nop 0
	v_mul_f32_e32 v136, v137, v136
	v_cvt_pk_bf16_f32 v137, v140, s0
	v_cvt_pk_bf16_f32 v136, v136, s0
	ds_write_b16 v198, v137 offset:6800
	ds_write_b16 v199, v136 offset:6800
	v_fma_f32 v136, v142, v242, v170
	v_fma_f32 v137, v138, v242, v171
	v_min_f32_e32 v136, v243, v136
	v_min_f32_e32 v137, v243, v137
	v_exp_f32_e32 v136, v136
	v_exp_f32_e32 v137, v137
	v_add_f32_e32 v136, 1.0, v136
	v_add_f32_e32 v137, 1.0, v137
	v_mul_f32_e32 v138, v136, v137
	v_rcp_f32_e32 v138, v138
	v_lshlrev_b32_e32 v140, 16, v232
	v_mul_f32_e32 v137, v137, v138
	v_mul_f32_e32 v137, v205, v137
	v_exp_f32_e32 v137, v137
	v_mul_f32_e32 v136, v136, v138
	v_mul_f32_e32 v136, v136, v140
	v_sub_f32_e32 v138, 1.0, v137
	v_add_f32_e32 v137, 1.0, v137
	v_mul_f32_e32 v137, v138, v137
	v_max_f32_e32 v137, 0, v137
	v_sqrt_f32_e32 v137, v137
	s_nop 0
	v_mul_f32_e32 v136, v137, v136
	v_cvt_pk_bf16_f32 v137, v138, s0
	v_cvt_pk_bf16_f32 v136, v136, s0
	ds_write_b16 v198, v137 offset:7200
	ds_write_b16 v199, v136 offset:7200
	v_fma_f32 v136, v143, v242, v170
	v_fma_f32 v137, v139, v242, v171
	v_min_f32_e32 v136, v243, v136
	v_min_f32_e32 v137, v243, v137
	v_exp_f32_e32 v136, v136
	v_exp_f32_e32 v137, v137
	v_add_f32_e32 v136, 1.0, v136
	v_add_f32_e32 v137, 1.0, v137
	v_mul_f32_e32 v138, v136, v137
	v_rcp_f32_e32 v138, v138
	v_lshlrev_b32_e32 v139, 16, v233
	v_mul_f32_e32 v137, v137, v138
	v_mul_f32_e32 v137, v205, v137
	v_exp_f32_e32 v137, v137
	v_mul_f32_e32 v136, v136, v138
	v_mul_f32_e32 v136, v136, v139
	v_sub_f32_e32 v138, 1.0, v137
	v_add_f32_e32 v137, 1.0, v137
	v_mul_f32_e32 v137, v138, v137
	v_max_f32_e32 v137, 0, v137
	v_sqrt_f32_e32 v137, v137
	s_nop 0
	v_mul_f32_e32 v136, v137, v136
	v_cvt_pk_bf16_f32 v136, v136, s0
	ds_write_b16 v199, v136 offset:7600
	v_cvt_pk_bf16_f32 v137, v138, s0
	ds_write_b16 v198, v137 offset:7600
	v_lshlrev_b32_e32 v137, 16, v234
	s_nop 0
	v_lshlrev_b32_e32 v125, 16, v235
	s_nop 0
	v_lshlrev_b32_e32 v124, 16, v236
	s_nop 0
	v_lshlrev_b32_e32 v123, 16, v237
	v_lshlrev_b32_e32 v123, 16, v238
	s_nop 0
	v_lshlrev_b32_e32 v123, 16, v239
	s_nop 0
	v_lshlrev_b32_e32 v123, 16, v240
	s_nop 0
	v_lshlrev_b32_e32 v123, 16, v241
	s_nop 0
	s_branch .LBB0_847
; #define LAS __attribute__((address_space(3)))
; DI unsigned pk2(float a, float b) { f32x2 v = {a, b}; bf2_t r = __builtin_convertvector(v, bf2_t); return __builtin_bit_cast(unsigned, r); }
; DI void phase_rglru(const Params& p, unsigned char* shm) {
;     ...
;                     for (int kk = 0; kk < 6; ++kk)
; #pragma unroll
;                         for (int mt = 0; mt < 4; ++mt) {
;                             const bf16x8 af = *(const LAS bf16x8*)(lds + XC + (16 * mt + fr) * TR + (32 * kk + 8 * fq) * 2);
;                             acc[mt][0] = __builtin_amdgcn_mfma_f32_16x16x32_bf16(af, Bf[u][kk], acc[mt][0], 0, 0, 0);
;                             acc[mt][1] = __builtin_amdgcn_mfma_f32_16x16x32_bf16(af, Bf[2 + u][kk], acc[mt][1], 0, 0, 0);
;                         }
;                     const int ch = chb + 16 * u + fr;
;                     const float ba = gb[ch], bx = gb[192 + ch], sp = gb[384 + ch];
; #pragma unroll
;                     for (int mt = 0; mt < 4; ++mt)
; #pragma unroll
;                         for (int j = 0; j < 4; ++j) {
;                             const int t = 16 * mt + 4 * fq + j;
;                             const float ea = 1.f + __expf(fminf(-(acc[mt][0][j] + ba), 40.f)), ex = 1.f + __expf(fminf(-(acc[mt][1][j] + bx), 40.f));
;                             const float inv = __builtin_amdgcn_rcpf(ea * ex);
;                             const float r = inv * ex, ig = inv * ea;
;                             const float av = __expf(r * sp), om = 1.f - av;
;                             const float xcv = __uint_as_float((unsigned)*(const LAS bf16_t*)(lds + XC + t * TR + ch * 2) << 16);
;                             const float bt = __builtin_amdgcn_sqrtf(fmaxf(om * (1.f + av), 0.f)) * (ig * xcv);
;                             *(LAS bf16_t*)(lds + LAo + t * TR + ch * 2) = (bf16_t)(pk2(om, 0.f) & 0xffffu);
;                             *(LAS bf16_t*)(lds + BTo + t * TR + ch * 2) = (bf16_t)(pk2(bt, 0.f) & 0xffffu);
;                         }
.Lgates_b:
	ds_read_b128 v[120:123], v204 offset:39680
	ds_read_b128 v[124:127], v204 offset:46080
	ds_read_b128 v[128:131], v204 offset:39744
	ds_read_b128 v[132:135], v204 offset:46144
	ds_read_b128 v[226:229], v204 offset:39808
	s_waitcnt lgkmcnt(4)
	v_mfma_f32_16x16x32_bf16 v[214:217], v[120:123], v[24:27], 0
	v_mfma_f32_16x16x32_bf16 v[210:213], v[120:123], v[72:75], 0
	ds_read_b128 v[230:233], v204 offset:46208
	s_waitcnt lgkmcnt(4)
	v_mfma_f32_16x16x32_bf16 v[218:221], v[124:127], v[24:27], 0
	v_mfma_f32_16x16x32_bf16 v[222:225], v[124:127], v[72:75], 0
	ds_read_b128 v[120:123], v204 offset:39872
	s_waitcnt lgkmcnt(4)
	v_mfma_f32_16x16x32_bf16 v[214:217], v[128:131], v[28:31], v[214:217]
	v_mfma_f32_16x16x32_bf16 v[210:213], v[128:131], v[76:79], v[210:213]
	ds_read_b128 v[124:127], v204 offset:46272
	s_waitcnt lgkmcnt(4)
	v_mfma_f32_16x16x32_bf16 v[218:221], v[132:135], v[28:31], v[218:221]
	v_mfma_f32_16x16x32_bf16 v[222:225], v[132:135], v[76:79], v[222:225]
	ds_read_b128 v[128:131], v204 offset:39936
	s_waitcnt lgkmcnt(4)
	v_mfma_f32_16x16x32_bf16 v[214:217], v[226:229], v[32:35], v[214:217]
	v_mfma_f32_16x16x32_bf16 v[210:213], v[226:229], v[80:83], v[210:213]
	ds_read_b128 v[132:135], v204 offset:46336
	s_waitcnt lgkmcnt(4)
	v_mfma_f32_16x16x32_bf16 v[218:221], v[230:233], v[32:35], v[218:221]
	v_mfma_f32_16x16x32_bf16 v[222:225], v[230:233], v[80:83], v[222:225]
	s_waitcnt lgkmcnt(3)
	v_mfma_f32_16x16x32_bf16 v[214:217], v[120:123], v[36:39], v[214:217]
	v_mfma_f32_16x16x32_bf16 v[210:213], v[120:123], v[84:87], v[210:213]
	s_waitcnt lgkmcnt(2)
	v_mfma_f32_16x16x32_bf16 v[218:221], v[124:127], v[36:39], v[218:221]
	v_mfma_f32_16x16x32_bf16 v[222:225], v[124:127], v[84:87], v[222:225]
	s_waitcnt lgkmcnt(1)
	v_mfma_f32_16x16x32_bf16 v[214:217], v[128:131], v[40:43], v[214:217]
	v_mfma_f32_16x16x32_bf16 v[210:213], v[128:131], v[88:91], v[210:213]
	s_waitcnt lgkmcnt(0)
	v_mfma_f32_16x16x32_bf16 v[218:221], v[132:135], v[40:43], v[218:221]
	v_mfma_f32_16x16x32_bf16 v[222:225], v[132:135], v[88:91], v[222:225]
	ds_read_b128 v[120:123], v204 offset:40000
	s_nop 1
	ds_read_b128 v[128:131], v204 offset:46400
	ds_read2st64_b32 v[170:171], v185 offset1:3
	ds_read_b32 v205, v185 offset:1536
	ds_read_u16 v226, v197 offset:26880
	ds_read_u16 v227, v197 offset:27280
	ds_read_u16 v228, v197 offset:27680
	ds_read_u16 v229, v197 offset:28080
	ds_read_u16 v230, v197 offset:33280
	ds_read_u16 v231, v197 offset:33680
	ds_read_u16 v232, v197 offset:34080
	ds_read_u16 v233, v197 offset:34480
	ds_read_u16 v234, v197 offset:39680
	ds_read_u16 v235, v197 offset:40080
	ds_read_u16 v236, v197 offset:40480
	ds_read_u16 v237, v197 offset:40880
	ds_read_u16 v238, v197 offset:46080
	ds_read_u16 v239, v197 offset:46480
	ds_read_u16 v240, v197 offset:46880
	ds_read_u16 v241, v197 offset:47280
	s_waitcnt lgkmcnt(15)
	v_mov_b32_e32 v242, 0xbfb8aa3b
	v_mov_b32_e32 v243, 0x4266d4ca
	v_mul_f32_e32 v170, v242, v170
	v_mul_f32_e32 v171, v242, v171
	v_mul_f32_e32 v205, 0x3fb8aa3b, v205
	v_mfma_f32_16x16x32_bf16 v[124:127], v[120:123], v[44:47], v[214:217]
	v_mfma_f32_16x16x32_bf16 v[120:123], v[120:123], v[92:95], v[210:213]
	s_waitcnt lgkmcnt(0)
	s_nop 6
	v_lshlrev_b32_e32 v211, 16, v226
	v_lshlrev_b32_e32 v149, 16, v227
	v_lshlrev_b32_e32 v148, 16, v228
	v_lshlrev_b32_e32 v147, 16, v229
	v_fma_f32 v124, v124, v242, v170
	v_fma_f32 v120, v120, v242, v171
	v_min_f32_e32 v124, v243, v124
	v_min_f32_e32 v120, v243, v120
	v_exp_f32_e32 v124, v124
	v_exp_f32_e32 v120, v120
	v_add_f32_e32 v124, 1.0, v124
	v_lshlrev_b32_e32 v145, 16, v230
	v_add_f32_e32 v120, 1.0, v120
	v_lshlrev_b32_e32 v141, 16, v231
	v_fma_f32 v121, v121, v242, v171
	v_min_f32_e32 v121, v243, v121
	v_exp_f32_e32 v121, v121
	v_mfma_f32_16x16x32_bf16 v[132:135], v[128:131], v[44:47], v[218:221]
	v_add_f32_e32 v121, 1.0, v121
	v_lshlrev_b32_e32 v140, 16, v232
	v_mfma_f32_16x16x32_bf16 v[128:131], v[128:131], v[92:95], v[222:225]
	s_nop 0
	v_lshlrev_b32_e32 v139, 16, v233
	s_nop 0
	v_mul_f32_e32 v136, v124, v120
	v_rcp_f32_e32 v136, v136
	s_nop 0
	v_mul_f32_e32 v120, v120, v136
	v_mul_f32_e32 v120, v205, v120
	v_exp_f32_e32 v120, v120
	v_mul_f32_e32 v124, v124, v136
	v_lshlrev_b32_e32 v137, 16, v234
	v_mul_f32_e32 v124, v124, v137
	v_sub_f32_e32 v136, 1.0, v120
	v_add_f32_e32 v120, 1.0, v120
	v_mul_f32_e32 v120, v136, v120
	v_max_f32_e32 v120, 0, v120
	v_sqrt_f32_e32 v120, v120
	s_nop 0
	v_mul_f32_e32 v120, v120, v124
	v_cvt_pk_bf16_f32 v120, v120, s0
	ds_write_b16 v199, v120 offset:12800
	v_fma_f32 v120, v125, v242, v170
	v_min_f32_e32 v120, v243, v120
	v_exp_f32_e32 v120, v120
	v_cvt_pk_bf16_f32 v124, v136, s0
	ds_write_b16 v198, v124 offset:12800
	v_add_f32_e32 v120, 1.0, v120
	v_mul_f32_e32 v124, v120, v121
	v_rcp_f32_e32 v124, v124
	v_lshlrev_b32_e32 v125, 16, v235
	v_mul_f32_e32 v121, v121, v124
	v_mul_f32_e32 v121, v205, v121
	v_exp_f32_e32 v121, v121
	v_mul_f32_e32 v120, v120, v124
	v_mul_f32_e32 v120, v120, v125
	v_sub_f32_e32 v124, 1.0, v121
	v_add_f32_e32 v121, 1.0, v121
	v_mul_f32_e32 v121, v124, v121
	v_max_f32_e32 v121, 0, v121
	v_sqrt_f32_e32 v121, v121
	s_nop 0
; #define LAS __attribute__((address_space(3)))
; DI unsigned pk2(float a, float b) { f32x2 v = {a, b}; bf2_t r = __builtin_convertvector(v, bf2_t); return __builtin_bit_cast(unsigned, r); }
; DI void phase_rglru(const Params& p, unsigned char* shm) {
;     ...
;                     const float ba = gb[ch], bx = gb[192 + ch], sp = gb[384 + ch];
; #pragma unroll
;                     for (int mt = 0; mt < 4; ++mt)
; #pragma unroll
;                         for (int j = 0; j < 4; ++j) {
;                             const int t = 16 * mt + 4 * fq + j;
;                             const float ea = 1.f + __expf(fminf(-(acc[mt][0][j] + ba), 40.f)), ex = 1.f + __expf(fminf(-(acc[mt][1][j] + bx), 40.f));
;                             const float inv = __builtin_amdgcn_rcpf(ea * ex);
;                             const float r = inv * ex, ig = inv * ea;
;                             const float av = __expf(r * sp), om = 1.f - av;
;                             const float xcv = __uint_as_float((unsigned)*(const LAS bf16_t*)(lds + XC + t * TR + ch * 2) << 16);
;                             const float bt = __builtin_amdgcn_sqrtf(fmaxf(om * (1.f + av), 0.f)) * (ig * xcv);
;                             *(LAS bf16_t*)(lds + LAo + t * TR + ch * 2) = (bf16_t)(pk2(om, 0.f) & 0xffffu);
;                             *(LAS bf16_t*)(lds + BTo + t * TR + ch * 2) = (bf16_t)(pk2(bt, 0.f) & 0xffffu);
;                         }
	v_mul_f32_e32 v120, v121, v120
	v_cvt_pk_bf16_f32 v121, v124, s0
	v_cvt_pk_bf16_f32 v120, v120, s0
	ds_write_b16 v198, v121 offset:13200
	ds_write_b16 v199, v120 offset:13200
	v_fma_f32 v120, v126, v242, v170
	v_fma_f32 v121, v122, v242, v171
	v_min_f32_e32 v120, v243, v120
	v_min_f32_e32 v121, v243, v121
	v_exp_f32_e32 v120, v120
	v_exp_f32_e32 v121, v121
	v_add_f32_e32 v120, 1.0, v120
	v_add_f32_e32 v121, 1.0, v121
	v_mul_f32_e32 v122, v120, v121
	v_rcp_f32_e32 v122, v122
	v_lshlrev_b32_e32 v124, 16, v236
	v_mul_f32_e32 v121, v121, v122
	v_mul_f32_e32 v121, v205, v121
	v_exp_f32_e32 v121, v121
	v_mul_f32_e32 v120, v120, v122
	v_mul_f32_e32 v120, v120, v124
	v_sub_f32_e32 v122, 1.0, v121
	v_add_f32_e32 v121, 1.0, v121
	v_mul_f32_e32 v121, v122, v121
	v_max_f32_e32 v121, 0, v121
	v_sqrt_f32_e32 v121, v121
	s_nop 0
	v_mul_f32_e32 v120, v121, v120
	v_cvt_pk_bf16_f32 v121, v122, s0
	v_cvt_pk_bf16_f32 v120, v120, s0
	ds_write_b16 v198, v121 offset:13600
	ds_write_b16 v199, v120 offset:13600
	v_fma_f32 v120, v127, v242, v170
	v_fma_f32 v121, v123, v242, v171
	v_min_f32_e32 v120, v243, v120
	v_min_f32_e32 v121, v243, v121
	v_exp_f32_e32 v120, v120
	v_exp_f32_e32 v121, v121
	v_add_f32_e32 v120, 1.0, v120
	v_add_f32_e32 v121, 1.0, v121
	v_mul_f32_e32 v122, v120, v121
	v_rcp_f32_e32 v122, v122
	v_lshlrev_b32_e32 v123, 16, v237
	v_mul_f32_e32 v121, v121, v122
	v_mul_f32_e32 v121, v205, v121
	v_exp_f32_e32 v121, v121
	v_mul_f32_e32 v120, v120, v122
	v_mul_f32_e32 v120, v120, v123
	v_sub_f32_e32 v122, 1.0, v121
	v_add_f32_e32 v121, 1.0, v121
	v_mul_f32_e32 v121, v122, v121
	v_max_f32_e32 v121, 0, v121
	v_sqrt_f32_e32 v121, v121
	v_lshlrev_b32_e32 v123, 16, v238
	v_mul_f32_e32 v120, v121, v120
	v_cvt_pk_bf16_f32 v121, v122, s0
	v_cvt_pk_bf16_f32 v120, v120, s0
	ds_write_b16 v198, v121 offset:14000
	ds_write_b16 v199, v120 offset:14000
	v_fma_f32 v120, v132, v242, v170
	v_fma_f32 v121, v128, v242, v171
	v_min_f32_e32 v120, v243, v120
	v_min_f32_e32 v121, v243, v121
	v_exp_f32_e32 v120, v120
	v_exp_f32_e32 v121, v121
	v_add_f32_e32 v120, 1.0, v120
	v_add_f32_e32 v121, 1.0, v121
	v_mul_f32_e32 v122, v120, v121
	v_rcp_f32_e32 v122, v122
	s_nop 0
	v_mul_f32_e32 v121, v121, v122
	v_mul_f32_e32 v121, v205, v121
	v_exp_f32_e32 v121, v121
	v_mul_f32_e32 v120, v120, v122
	v_mul_f32_e32 v120, v120, v123
	v_sub_f32_e32 v122, 1.0, v121
	v_add_f32_e32 v121, 1.0, v121
	v_mul_f32_e32 v121, v122, v121
	v_max_f32_e32 v121, 0, v121
	v_sqrt_f32_e32 v121, v121
	v_lshlrev_b32_e32 v123, 16, v239
	v_mul_f32_e32 v120, v121, v120
	v_cvt_pk_bf16_f32 v121, v122, s0
	v_cvt_pk_bf16_f32 v120, v120, s0
	ds_write_b16 v198, v121 offset:19200
	ds_write_b16 v199, v120 offset:19200
	v_fma_f32 v120, v133, v242, v170
	v_fma_f32 v121, v129, v242, v171
	v_min_f32_e32 v120, v243, v120
	v_min_f32_e32 v121, v243, v121
	v_exp_f32_e32 v120, v120
	v_exp_f32_e32 v121, v121
	v_add_f32_e32 v120, 1.0, v120
	v_add_f32_e32 v121, 1.0, v121
	v_mul_f32_e32 v122, v120, v121
	v_rcp_f32_e32 v122, v122
	s_nop 0
	v_mul_f32_e32 v121, v121, v122
	v_mul_f32_e32 v121, v205, v121
	v_exp_f32_e32 v121, v121
	v_mul_f32_e32 v120, v120, v122
	v_mul_f32_e32 v120, v120, v123
	v_sub_f32_e32 v122, 1.0, v121
	v_add_f32_e32 v121, 1.0, v121
	v_mul_f32_e32 v121, v122, v121
	v_max_f32_e32 v121, 0, v121
	v_sqrt_f32_e32 v121, v121
	v_lshlrev_b32_e32 v123, 16, v240
	v_mul_f32_e32 v120, v121, v120
	v_cvt_pk_bf16_f32 v121, v122, s0
	v_cvt_pk_bf16_f32 v120, v120, s0
	ds_write_b16 v198, v121 offset:19600
	ds_write_b16 v199, v120 offset:19600
	v_fma_f32 v120, v134, v242, v170
	v_fma_f32 v121, v130, v242, v171
	v_min_f32_e32 v120, v243, v120
	v_min_f32_e32 v121, v243, v121
	v_exp_f32_e32 v120, v120
	v_exp_f32_e32 v121, v121
	v_add_f32_e32 v120, 1.0, v120
	v_add_f32_e32 v121, 1.0, v121
	v_mul_f32_e32 v122, v120, v121
	v_rcp_f32_e32 v122, v122
	s_nop 0
	v_mul_f32_e32 v121, v121, v122
	v_mul_f32_e32 v121, v205, v121
	v_exp_f32_e32 v121, v121
	v_mul_f32_e32 v120, v120, v122
	v_mul_f32_e32 v120, v120, v123
	v_sub_f32_e32 v122, 1.0, v121
	v_add_f32_e32 v121, 1.0, v121
	v_mul_f32_e32 v121, v122, v121
	v_max_f32_e32 v121, 0, v121
	v_sqrt_f32_e32 v121, v121
	v_lshlrev_b32_e32 v123, 16, v241
	v_mul_f32_e32 v120, v121, v120
	v_cvt_pk_bf16_f32 v121, v122, s0
	v_cvt_pk_bf16_f32 v120, v120, s0
	ds_write_b16 v198, v121 offset:20000
	ds_write_b16 v199, v120 offset:20000
	v_fma_f32 v120, v135, v242, v170
	v_fma_f32 v121, v131, v242, v171
	v_min_f32_e32 v120, v243, v120
	v_min_f32_e32 v121, v243, v121
	v_exp_f32_e32 v120, v120
	v_exp_f32_e32 v121, v121
	v_add_f32_e32 v120, 1.0, v120
	v_add_f32_e32 v121, 1.0, v121
	v_mul_f32_e32 v122, v120, v121
	v_rcp_f32_e32 v122, v122
	s_nop 0
	v_mul_f32_e32 v121, v121, v122
	v_mul_f32_e32 v121, v205, v121
	v_mul_f32_e32 v120, v120, v122
	v_exp_f32_e32 v122, v121
	v_mul_f32_e32 v120, v120, v123
	v_sub_f32_e32 v121, 1.0, v122
	v_add_f32_e32 v122, 1.0, v122
	v_mul_f32_e32 v122, v121, v122
	v_max_f32_e32 v122, 0, v122
	v_sqrt_f32_e32 v122, v122
	v_cvt_pk_bf16_f32 v121, v121, s0
	ds_write_b16 v198, v121 offset:20400
	v_mul_f32_e32 v120, v122, v120
	v_cvt_pk_bf16_f32 v120, v120, s0
	ds_write_b16 v199, v120 offset:20400
